# k37: k20 + nontemporal hint on the FFN-out epilogue's residual tile loads (cache policy)
# baseline (speedup 1.0000x reference)
; #define PG8_STAGE(bufoff, gbase, voff) do { _Pragma("unroll") for (int _i = 0; _i < 2; ++_i) \
;         __builtin_amdgcn_global_load_lds((const unsigned*)((const char*)(gbase) + (voff)[_i]), (LAS unsigned*)(lds + (bufoff) + ldsw + _i * 8192), 16, 0, 0); } while (0)
; #define PG8_LDA(dst, b, h) do { _Pragma("unroll") for (int m = 0; m < 4; ++m) _Pragma("unroll") for (int k = 0; k < 2; ++k) dst[m][k] = *(const LAS bf16x8*)(lds + PG8_SA(b, h) + aoff + m * 2048 + k * 1024); } while (0)
; #define PG8_LDB(dst, b, h) do { _Pragma("unroll") for (int n = 0; n < 2; ++n) _Pragma("unroll") for (int k = 0; k < 2; ++k) dst[n][k] = *(const LAS bf16x8*)(lds + PG8_SB(b, h) + boff + n * 2048 + k * 1024); } while (0)
; #define PG8_MMA(ai, bj, At, Bt) do { __builtin_amdgcn_s_setprio(1); _Pragma("unroll") for (int m = 0; m < 4; ++m) _Pragma("unroll") for (int n = 0; n < 2; ++n) _Pragma("unroll") for (int k = 0; k < 2; ++k) \
;         acc[ai][bj][m][n] = __builtin_amdgcn_mfma_f32_16x16x32_bf16(Bt[n][k], At[m][k], acc[ai][bj][m][n], 0, 0, 0); __builtin_amdgcn_s_setprio(0); } while (0)
; #define PG8_WAIT_V(n) asm volatile("s_waitcnt vmcnt(" #n ")" ::: "memory")
; #define PG8_WAIT_L(n) asm volatile("s_waitcnt lgkmcnt(" #n ")" ::: "memory")
; #define PG8_BAR __builtin_amdgcn_s_barrier()
; template <class Epi>
; __device__ __forceinline__ void gemm_phase(LAS unsigned char* lds, const Gemm g, const Epi& E) {
;     ...
;         for (int t = 0; t < nt; t += 2) {
;             const bool last = (t == nt - 2);
;             const char* a1 = cA + (size_t)(t + 1) * kstep;
;             const char* a2 = last ? nA : cA + (size_t)(t + 2) * kstep; const char* b2 = last ? nB : cB + (size_t)(t + 2) * kstep;
;             const char* a3 = a2 + kstep; const char* b3 = b2 + kstep;
;             PG8_LDB(B0, 0, 0); PG8_SCHED; PG8_LDA(At, 0, 0); PG8_STAGE(PG8_SA(1, 1), a1 + hstepA, voffA);
;             PG8_WAIT_L(8); PG8_BAR; PG8_WAIT_L(0); PG8_MMA(0, 0, At, B0); PG8_BAR; PG8_SCHED;
;             PG8_LDB(B1, 0, 1); PG8_STAGE(PG8_SB(0, 0), b2, voffB);
;             PG8_BAR; PG8_WAIT_L(0); PG8_MMA(0, 1, At, B1); PG8_BAR;
;             PG8_LDA(At, 0, 1); PG8_STAGE(PG8_SA(0, 0), a2, voffA);
;             PG8_BAR; PG8_WAIT_L(0); PG8_MMA(1, 0, At, B0); PG8_BAR; PG8_SCHED;
;             PG8_STAGE(PG8_SB(0, 1), b2 + hstepB, voffB);
;             PG8_WAIT_V(6); PG8_BAR; PG8_MMA(1, 1, At, B1); PG8_BAR;
.LBB0_547:
	s_add_u32 s10, s8, 0x100
	s_addc_u32 s11, s9, 0
	s_add_i32 s26, 0, 0x10000
	v_add_u32_e32 v142, s26, v157
	ds_read_b128 v[130:133], v142
	ds_read_b128 v[134:137], v142 offset:1024
	ds_read_b128 v[138:141], v142 offset:2048
	ds_read_b128 v[142:145], v142 offset:3072
	s_cmp_eq_u32 s67, 40
	s_cselect_b32 s15, s5, s11
	s_cselect_b32 s14, s4, s10
	s_cselect_b32 s13, s7, s66
	s_cselect_b32 s12, s6, s65
	v_lshl_add_u64 v[154:155], s[8:9], 0, v[150:151]
	s_add_i32 m0, s29, 0xc000
	ds_read_b128 v[160:163], v158
	ds_read_b128 v[164:167], v158 offset:1024
	ds_read_b128 v[168:171], v158 offset:2048
	ds_read_b128 v[172:175], v158 offset:3072
	ds_read_b128 v[180:183], v158 offset:4096
	ds_read_b128 v[184:187], v158 offset:5120
	ds_read_b128 v[188:191], v158 offset:6144
	ds_read_b128 v[192:195], v158 offset:7168
	global_load_lds_dwordx4 v[154:155], off
	v_lshl_add_u64 v[154:155], s[8:9], 0, v[152:153]
	s_add_i32 m0, s29, 0xe000
	s_nop 0
	global_load_lds_dwordx4 v[154:155], off
	s_waitcnt lgkmcnt(8)
	s_barrier
	s_waitcnt lgkmcnt(0)
	v_mfma_f32_16x16x32_bf16 v[126:129], v[130:133], v[160:163], v[126:129]
	v_mfma_f32_16x16x32_bf16 v[122:125], v[138:141], v[160:163], v[122:125]
	v_mfma_f32_16x16x32_bf16 v[118:121], v[130:133], v[168:171], v[118:121]
	v_mfma_f32_16x16x32_bf16 v[110:113], v[138:141], v[168:171], v[110:113]
	v_mfma_f32_16x16x32_bf16 v[102:105], v[130:133], v[180:183], v[102:105]
	v_mfma_f32_16x16x32_bf16 v[94:97], v[138:141], v[180:183], v[94:97]
	v_mfma_f32_16x16x32_bf16 v[86:89], v[130:133], v[188:191], v[86:89]
	v_mfma_f32_16x16x32_bf16 v[78:81], v[138:141], v[188:191], v[78:81]
	v_mfma_f32_16x16x32_bf16 v[126:129], v[134:137], v[164:167], v[126:129]
	v_mfma_f32_16x16x32_bf16 v[122:125], v[142:145], v[164:167], v[122:125]
	v_mfma_f32_16x16x32_bf16 v[118:121], v[134:137], v[172:175], v[118:121]
	v_mfma_f32_16x16x32_bf16 v[110:113], v[142:145], v[172:175], v[110:113]
	v_mfma_f32_16x16x32_bf16 v[102:105], v[134:137], v[184:187], v[102:105]
	v_mfma_f32_16x16x32_bf16 v[94:97], v[142:145], v[184:187], v[94:97]
	v_mfma_f32_16x16x32_bf16 v[86:89], v[134:137], v[192:195], v[86:89]
	v_mfma_f32_16x16x32_bf16 v[78:81], v[142:145], v[192:195], v[78:81]
	s_barrier
	s_add_i32 s27, 0, 0x14000
	v_add_u32_e32 v154, s27, v157
	s_add_i32 s8, s26, s18
	ds_read_b128 v[196:199], v154
	ds_read_b128 v[200:203], v154 offset:1024
	ds_read_b128 v[204:207], v154 offset:2048
	ds_read_b128 v[226:229], v154 offset:3072
	v_lshl_add_u64 v[154:155], s[12:13], 0, v[148:149]
	s_mov_b32 m0, s8
	v_lshl_add_u64 v[176:177], s[12:13], 0, v[146:147]
	global_load_lds_dwordx4 v[154:155], off
	s_add_i32 m0, s8, 0x2000
	s_nop 0
	global_load_lds_dwordx4 v[176:177], off
	s_nop 1
	s_mov_b32 m0, s29
	v_lshl_add_u64 v[208:209], s[14:15], 0, v[148:149]
	s_barrier
	s_waitcnt lgkmcnt(0)
	v_mfma_f32_16x16x32_bf16 v[114:117], v[196:199], v[160:163], v[114:117]
	v_mfma_f32_16x16x32_bf16 v[106:109], v[204:207], v[160:163], v[106:109]
	v_mfma_f32_16x16x32_bf16 v[98:101], v[196:199], v[168:171], v[98:101]
	v_mfma_f32_16x16x32_bf16 v[90:93], v[204:207], v[168:171], v[90:93]
	v_mfma_f32_16x16x32_bf16 v[82:85], v[196:199], v[180:183], v[82:85]
	v_mfma_f32_16x16x32_bf16 v[74:77], v[204:207], v[180:183], v[74:77]
	v_mfma_f32_16x16x32_bf16 v[70:73], v[196:199], v[188:191], v[70:73]
	v_mfma_f32_16x16x32_bf16 v[66:69], v[204:207], v[188:191], v[66:69]
	v_mfma_f32_16x16x32_bf16 v[114:117], v[200:203], v[164:167], v[114:117]
	v_mfma_f32_16x16x32_bf16 v[106:109], v[226:229], v[164:167], v[106:109]
	v_mfma_f32_16x16x32_bf16 v[98:101], v[200:203], v[172:175], v[98:101]
	v_mfma_f32_16x16x32_bf16 v[90:93], v[226:229], v[172:175], v[90:93]
	v_mfma_f32_16x16x32_bf16 v[82:85], v[200:203], v[184:187], v[82:85]
	v_mfma_f32_16x16x32_bf16 v[74:77], v[226:229], v[184:187], v[74:77]
	v_mfma_f32_16x16x32_bf16 v[70:73], v[200:203], v[192:195], v[70:73]
	v_mfma_f32_16x16x32_bf16 v[66:69], v[226:229], v[192:195], v[66:69]
	s_barrier
	ds_read_b128 v[160:163], v158 offset:16384
	ds_read_b128 v[164:167], v158 offset:17408
	ds_read_b128 v[168:171], v158 offset:18432
	ds_read_b128 v[172:175], v158 offset:19456
	ds_read_b128 v[180:183], v158 offset:20480
	ds_read_b128 v[184:187], v158 offset:21504
	ds_read_b128 v[188:191], v158 offset:22528
	ds_read_b128 v[192:195], v158 offset:23552
	global_load_lds_dwordx4 v[208:209], off
	v_lshl_add_u64 v[230:231], s[14:15], 0, v[146:147]
	s_mov_b32 m0, s30
	s_nop 0
	global_load_lds_dwordx4 v[230:231], off
	s_barrier
	s_waitcnt lgkmcnt(0)
	v_mfma_f32_16x16x32_bf16 v[62:65], v[130:133], v[160:163], v[62:65]
	v_mfma_f32_16x16x32_bf16 v[58:61], v[138:141], v[160:163], v[58:61]
	v_mfma_f32_16x16x32_bf16 v[54:57], v[130:133], v[168:171], v[54:57]
	v_mfma_f32_16x16x32_bf16 v[46:49], v[138:141], v[168:171], v[46:49]
	v_mfma_f32_16x16x32_bf16 v[38:41], v[130:133], v[180:183], v[38:41]
	v_mfma_f32_16x16x32_bf16 v[30:33], v[138:141], v[180:183], v[30:33]
	v_mfma_f32_16x16x32_bf16 v[22:25], v[130:133], v[188:191], v[22:25]
	v_mfma_f32_16x16x32_bf16 v[14:17], v[138:141], v[188:191], v[14:17]
	v_mfma_f32_16x16x32_bf16 v[62:65], v[134:137], v[164:167], v[62:65]
	v_mfma_f32_16x16x32_bf16 v[58:61], v[142:145], v[164:167], v[58:61]
	v_mfma_f32_16x16x32_bf16 v[54:57], v[134:137], v[172:175], v[54:57]
	v_mfma_f32_16x16x32_bf16 v[46:49], v[142:145], v[172:175], v[46:49]
	v_mfma_f32_16x16x32_bf16 v[38:41], v[134:137], v[184:187], v[38:41]
	v_mfma_f32_16x16x32_bf16 v[30:33], v[142:145], v[184:187], v[30:33]
	v_mfma_f32_16x16x32_bf16 v[22:25], v[134:137], v[192:195], v[22:25]
	v_mfma_f32_16x16x32_bf16 v[14:17], v[142:145], v[192:195], v[14:17]
	s_barrier
; #define PG8_STAGE(bufoff, gbase, voff) do { _Pragma("unroll") for (int _i = 0; _i < 2; ++_i) \
;         __builtin_amdgcn_global_load_lds((const unsigned*)((const char*)(gbase) + (voff)[_i]), (LAS unsigned*)(lds + (bufoff) + ldsw + _i * 8192), 16, 0, 0); } while (0)
; #define PG8_LDA(dst, b, h) do { _Pragma("unroll") for (int m = 0; m < 4; ++m) _Pragma("unroll") for (int k = 0; k < 2; ++k) dst[m][k] = *(const LAS bf16x8*)(lds + PG8_SA(b, h) + aoff + m * 2048 + k * 1024); } while (0)
; #define PG8_LDB(dst, b, h) do { _Pragma("unroll") for (int n = 0; n < 2; ++n) _Pragma("unroll") for (int k = 0; k < 2; ++k) dst[n][k] = *(const LAS bf16x8*)(lds + PG8_SB(b, h) + boff + n * 2048 + k * 1024); } while (0)
; #define PG8_MMA(ai, bj, At, Bt) do { __builtin_amdgcn_s_setprio(1); _Pragma("unroll") for (int m = 0; m < 4; ++m) _Pragma("unroll") for (int n = 0; n < 2; ++n) _Pragma("unroll") for (int k = 0; k < 2; ++k) \
;         acc[ai][bj][m][n] = __builtin_amdgcn_mfma_f32_16x16x32_bf16(Bt[n][k], At[m][k], acc[ai][bj][m][n], 0, 0, 0); __builtin_amdgcn_s_setprio(0); } while (0)
; #define PG8_WAIT_V(n) asm volatile("s_waitcnt vmcnt(" #n ")" ::: "memory")
; #define PG8_WAIT_L(n) asm volatile("s_waitcnt lgkmcnt(" #n ")" ::: "memory")
; #define PG8_BAR __builtin_amdgcn_s_barrier()
; #define PG8_SCHED __builtin_amdgcn_sched_barrier(0)
; template <class Epi>
; __device__ __forceinline__ void gemm_phase(LAS unsigned char* lds, const Gemm g, const Epi& E) {
;     ...
;             PG8_BAR; PG8_WAIT_L(0); PG8_MMA(1, 0, At, B0); PG8_BAR; PG8_SCHED;
;             PG8_STAGE(PG8_SB(0, 1), b2 + hstepB, voffB);
;             PG8_WAIT_V(6); PG8_BAR; PG8_MMA(1, 1, At, B1); PG8_BAR;
;             PG8_LDB(B0, 1, 0); PG8_SCHED; PG8_LDA(At, 1, 0); PG8_STAGE(PG8_SA(0, 1), a2 + hstepA, voffA);
;             PG8_WAIT_L(8); PG8_BAR; PG8_WAIT_L(0); PG8_MMA(0, 0, At, B0); PG8_BAR; PG8_SCHED;
;             PG8_LDB(B1, 1, 1); PG8_STAGE(PG8_SB(1, 0), b3, voffB);
;             PG8_BAR; PG8_WAIT_L(0); PG8_MMA(0, 1, At, B1); PG8_BAR;
;             PG8_LDA(At, 1, 1); PG8_STAGE(PG8_SA(1, 0), a3, voffA);
;             PG8_BAR; PG8_WAIT_L(0); PG8_MMA(1, 0, At, B0); PG8_BAR; PG8_SCHED;
	s_add_u32 s8, s12, 0xb0000
	s_addc_u32 s9, s13, 0
	s_add_i32 s26, s27, s18
	v_lshl_add_u64 v[130:131], s[8:9], 0, v[148:149]
	s_mov_b32 m0, s26
	s_nop 0
	global_load_lds_dwordx4 v[130:131], off
	v_lshl_add_u64 v[130:131], s[8:9], 0, v[146:147]
	s_add_i32 m0, s26, 0x2000
	s_nop 0
	global_load_lds_dwordx4 v[130:131], off
	s_add_i32 s26, 0, 0x18000
	v_add_u32_e32 v142, s26, v157
	s_waitcnt vmcnt(6)
	s_barrier
	v_mfma_f32_16x16x32_bf16 v[50:53], v[196:199], v[160:163], v[50:53]
	v_mfma_f32_16x16x32_bf16 v[42:45], v[204:207], v[160:163], v[42:45]
	v_mfma_f32_16x16x32_bf16 v[34:37], v[196:199], v[168:171], v[34:37]
	v_mfma_f32_16x16x32_bf16 v[26:29], v[204:207], v[168:171], v[26:29]
	v_mfma_f32_16x16x32_bf16 v[18:21], v[196:199], v[180:183], v[18:21]
	v_mfma_f32_16x16x32_bf16 v[10:13], v[204:207], v[180:183], v[10:13]
	v_mfma_f32_16x16x32_bf16 v[6:9], v[196:199], v[188:191], v[6:9]
	v_mfma_f32_16x16x32_bf16 v[2:5], v[204:207], v[188:191], v[2:5]
	v_mfma_f32_16x16x32_bf16 v[50:53], v[200:203], v[164:167], v[50:53]
	v_mfma_f32_16x16x32_bf16 v[42:45], v[226:229], v[164:167], v[42:45]
	v_mfma_f32_16x16x32_bf16 v[34:37], v[200:203], v[172:175], v[34:37]
	v_mfma_f32_16x16x32_bf16 v[26:29], v[226:229], v[172:175], v[26:29]
	v_mfma_f32_16x16x32_bf16 v[18:21], v[200:203], v[184:187], v[18:21]
	v_mfma_f32_16x16x32_bf16 v[10:13], v[226:229], v[184:187], v[10:13]
	v_mfma_f32_16x16x32_bf16 v[6:9], v[200:203], v[192:195], v[6:9]
	v_mfma_f32_16x16x32_bf16 v[2:5], v[226:229], v[192:195], v[2:5]
	s_barrier
	ds_read_b128 v[130:133], v142
	ds_read_b128 v[134:137], v142 offset:1024
	ds_read_b128 v[138:141], v142 offset:2048
	ds_read_b128 v[142:145], v142 offset:3072
	s_add_u32 s8, s14, 0xb0000
	s_addc_u32 s9, s15, 0
	s_mov_b32 m0, s31
	v_lshl_add_u64 v[196:197], s[8:9], 0, v[148:149]
	ds_read_b128 v[160:163], v158 offset:32768
	ds_read_b128 v[164:167], v158 offset:33792
	ds_read_b128 v[168:171], v158 offset:34816
	ds_read_b128 v[172:175], v158 offset:35840
	ds_read_b128 v[180:183], v158 offset:36864
	ds_read_b128 v[184:187], v158 offset:37888
	ds_read_b128 v[188:191], v158 offset:38912
	ds_read_b128 v[192:195], v158 offset:39936
	global_load_lds_dwordx4 v[196:197], off
	v_lshl_add_u64 v[196:197], s[8:9], 0, v[146:147]
	s_mov_b32 m0, s36
	s_nop 0
	global_load_lds_dwordx4 v[196:197], off
	s_waitcnt lgkmcnt(8)
	s_barrier
	s_waitcnt lgkmcnt(0)
	v_mfma_f32_16x16x32_bf16 v[126:129], v[130:133], v[160:163], v[126:129]
	v_mfma_f32_16x16x32_bf16 v[122:125], v[138:141], v[160:163], v[122:125]
	v_mfma_f32_16x16x32_bf16 v[118:121], v[130:133], v[168:171], v[118:121]
	v_mfma_f32_16x16x32_bf16 v[110:113], v[138:141], v[168:171], v[110:113]
	v_mfma_f32_16x16x32_bf16 v[102:105], v[130:133], v[180:183], v[102:105]
	v_mfma_f32_16x16x32_bf16 v[94:97], v[138:141], v[180:183], v[94:97]
	v_mfma_f32_16x16x32_bf16 v[86:89], v[130:133], v[188:191], v[86:89]
	v_mfma_f32_16x16x32_bf16 v[78:81], v[138:141], v[188:191], v[78:81]
	v_mfma_f32_16x16x32_bf16 v[126:129], v[134:137], v[164:167], v[126:129]
	v_mfma_f32_16x16x32_bf16 v[122:125], v[142:145], v[164:167], v[122:125]
	v_mfma_f32_16x16x32_bf16 v[118:121], v[134:137], v[172:175], v[118:121]
	v_mfma_f32_16x16x32_bf16 v[110:113], v[142:145], v[172:175], v[110:113]
	v_mfma_f32_16x16x32_bf16 v[102:105], v[134:137], v[184:187], v[102:105]
	v_mfma_f32_16x16x32_bf16 v[94:97], v[142:145], v[184:187], v[94:97]
	v_mfma_f32_16x16x32_bf16 v[86:89], v[134:137], v[192:195], v[86:89]
	v_mfma_f32_16x16x32_bf16 v[78:81], v[142:145], v[192:195], v[78:81]
	s_barrier
	s_add_i32 s14, 0, 0x1c000
	s_add_i32 s8, s26, s18
	v_add_u32_e32 v159, s14, v157
	v_lshl_add_u64 v[154:155], v[154:155], 0, s[86:87]
	s_mov_b32 m0, s8
	ds_read_b128 v[196:199], v159
	ds_read_b128 v[200:203], v159 offset:1024
	ds_read_b128 v[204:207], v159 offset:2048
	ds_read_b128 v[226:229], v159 offset:3072
	global_load_lds_dwordx4 v[154:155], off
	v_lshl_add_u64 v[154:155], v[176:177], 0, s[86:87]
	s_add_i32 m0, s8, 0x2000
	s_nop 0
	global_load_lds_dwordx4 v[154:155], off
	s_nop 1
	s_mov_b32 m0, s52
	v_lshl_add_u64 v[154:155], v[208:209], 0, s[86:87]
	s_barrier
	s_waitcnt lgkmcnt(0)
	v_mfma_f32_16x16x32_bf16 v[114:117], v[196:199], v[160:163], v[114:117]
	v_mfma_f32_16x16x32_bf16 v[106:109], v[204:207], v[160:163], v[106:109]
	v_mfma_f32_16x16x32_bf16 v[98:101], v[196:199], v[168:171], v[98:101]
	v_mfma_f32_16x16x32_bf16 v[90:93], v[204:207], v[168:171], v[90:93]
	v_mfma_f32_16x16x32_bf16 v[82:85], v[196:199], v[180:183], v[82:85]
	v_mfma_f32_16x16x32_bf16 v[74:77], v[204:207], v[180:183], v[74:77]
	v_mfma_f32_16x16x32_bf16 v[70:73], v[196:199], v[188:191], v[70:73]
	v_mfma_f32_16x16x32_bf16 v[66:69], v[204:207], v[188:191], v[66:69]
	v_mfma_f32_16x16x32_bf16 v[114:117], v[200:203], v[164:167], v[114:117]
	v_mfma_f32_16x16x32_bf16 v[106:109], v[226:229], v[164:167], v[106:109]
	v_mfma_f32_16x16x32_bf16 v[98:101], v[200:203], v[172:175], v[98:101]
	v_mfma_f32_16x16x32_bf16 v[90:93], v[226:229], v[172:175], v[90:93]
	v_mfma_f32_16x16x32_bf16 v[82:85], v[200:203], v[184:187], v[82:85]
	v_mfma_f32_16x16x32_bf16 v[74:77], v[226:229], v[184:187], v[74:77]
	v_mfma_f32_16x16x32_bf16 v[70:73], v[200:203], v[192:195], v[70:73]
	v_mfma_f32_16x16x32_bf16 v[66:69], v[226:229], v[192:195], v[66:69]
	s_barrier
	ds_read_b128 v[160:163], v158 offset:49152
	ds_read_b128 v[164:167], v158 offset:50176
	ds_read_b128 v[168:171], v158 offset:51200
	ds_read_b128 v[172:175], v158 offset:52224
	ds_read_b128 v[180:183], v158 offset:53248
	ds_read_b128 v[184:187], v158 offset:54272
	ds_read_b128 v[188:191], v158 offset:55296
	ds_read_b128 v[192:195], v158 offset:56320
	global_load_lds_dwordx4 v[154:155], off
	v_lshl_add_u64 v[154:155], v[230:231], 0, s[86:87]
	s_mov_b32 m0, s53
	s_nop 0
	global_load_lds_dwordx4 v[154:155], off
	s_barrier
; #define PG8_STAGE(bufoff, gbase, voff) do { _Pragma("unroll") for (int _i = 0; _i < 2; ++_i) \
;         __builtin_amdgcn_global_load_lds((const unsigned*)((const char*)(gbase) + (voff)[_i]), (LAS unsigned*)(lds + (bufoff) + ldsw + _i * 8192), 16, 0, 0); } while (0)
; #define PG8_MMA(ai, bj, At, Bt) do { __builtin_amdgcn_s_setprio(1); _Pragma("unroll") for (int m = 0; m < 4; ++m) _Pragma("unroll") for (int n = 0; n < 2; ++n) _Pragma("unroll") for (int k = 0; k < 2; ++k) \
;         acc[ai][bj][m][n] = __builtin_amdgcn_mfma_f32_16x16x32_bf16(Bt[n][k], At[m][k], acc[ai][bj][m][n], 0, 0, 0); __builtin_amdgcn_s_setprio(0); } while (0)
; #define PG8_WAIT_V(n) asm volatile("s_waitcnt vmcnt(" #n ")" ::: "memory")
; #define PG8_WAIT_L(n) asm volatile("s_waitcnt lgkmcnt(" #n ")" ::: "memory")
; #define PG8_BAR __builtin_amdgcn_s_barrier()
; template <class Epi>
; __device__ __forceinline__ void gemm_phase(LAS unsigned char* lds, const Gemm g, const Epi& E) {
;     ...
;             PG8_BAR; PG8_WAIT_L(0); PG8_MMA(1, 0, At, B0); PG8_BAR; PG8_SCHED;
;             PG8_STAGE(PG8_SB(1, 1), b3 + hstepB, voffB);
;             PG8_WAIT_V(6); PG8_BAR; PG8_MMA(1, 1, At, B1); PG8_BAR;
;     __device__ __forceinline__ void operator()(const AccT& acc, const Unit& u, int wr, int wc, int fr, int fq) const {
;         asm volatile("" : "+v"(fr), "+v"(fq));
;         const int gpm = mapA.src(u.pm);
;         const int mb = gpm < 32 ? 32 : (gpm - 32) >> 3;
;         const int row0 = gpm * 256 + wr * 64 + fr, col0 = u.pn * 256 + wc * 32 + 4 * fq;
;         const float* gp = modl + ((size_t)mb * 6 + gi) * 1024;
;         f32x4 gv[2][2];
; #pragma unroll
;         for (int bj = 0; bj < 2; ++bj)
; #pragma unroll
;             for (int n = 0; n < 2; ++n) { gv[bj][n] = *(const f32x4*)(gp + col0 + bj * 128 + n * 16); if (scale) gv[bj][n] = gv[bj][n] * *(const f32x4*)(scale + col0 + bj * 128 + n * 16); }
;         const float* sbase = (gpm < 32 ? Xc : Xl) + (size_t)row0 * 1024 + col0;
; #pragma unroll
;         for (int ai = 0; ai < 2; ++ai) {
;             f32x4 xo[4][2][2];
; #pragma unroll
;             for (int m = 0; m < 4; ++m)
; #pragma unroll
;                 for (int bj = 0; bj < 2; ++bj)
; #pragma unroll
;                     for (int n = 0; n < 2; ++n) xo[m][bj][n] = *(const f32x4*)(sbase + (size_t)(ai * 128 + m * 16) * 1024 + bj * 128 + n * 16);
	s_waitcnt lgkmcnt(0)
	v_mfma_f32_16x16x32_bf16 v[62:65], v[130:133], v[160:163], v[62:65]
	v_mfma_f32_16x16x32_bf16 v[58:61], v[138:141], v[160:163], v[58:61]
	v_mfma_f32_16x16x32_bf16 v[54:57], v[130:133], v[168:171], v[54:57]
	v_mfma_f32_16x16x32_bf16 v[46:49], v[138:141], v[168:171], v[46:49]
	v_mfma_f32_16x16x32_bf16 v[38:41], v[130:133], v[180:183], v[38:41]
	v_mfma_f32_16x16x32_bf16 v[30:33], v[138:141], v[180:183], v[30:33]
	v_mfma_f32_16x16x32_bf16 v[22:25], v[130:133], v[188:191], v[22:25]
	v_mfma_f32_16x16x32_bf16 v[14:17], v[138:141], v[188:191], v[14:17]
	v_mfma_f32_16x16x32_bf16 v[62:65], v[134:137], v[164:167], v[62:65]
	v_mfma_f32_16x16x32_bf16 v[58:61], v[142:145], v[164:167], v[58:61]
	v_mfma_f32_16x16x32_bf16 v[54:57], v[134:137], v[172:175], v[54:57]
	v_mfma_f32_16x16x32_bf16 v[46:49], v[142:145], v[172:175], v[46:49]
	v_mfma_f32_16x16x32_bf16 v[38:41], v[134:137], v[184:187], v[38:41]
	v_mfma_f32_16x16x32_bf16 v[30:33], v[142:145], v[184:187], v[30:33]
	v_mfma_f32_16x16x32_bf16 v[22:25], v[134:137], v[192:195], v[22:25]
	v_mfma_f32_16x16x32_bf16 v[14:17], v[142:145], v[192:195], v[14:17]
	s_barrier
	s_add_u32 s8, s12, 0xb0080
	s_addc_u32 s9, s13, 0
	s_add_i32 s12, s14, s18
	v_lshl_add_u64 v[130:131], s[8:9], 0, v[148:149]
	s_mov_b32 m0, s12
	s_nop 0
	global_load_lds_dwordx4 v[130:131], off
	v_lshl_add_u64 v[130:131], s[8:9], 0, v[146:147]
	s_add_i32 m0, s12, 0x2000
	s_nop 0
	global_load_lds_dwordx4 v[130:131], off
	s_waitcnt vmcnt(6)
	s_barrier
	v_mfma_f32_16x16x32_bf16 v[50:53], v[196:199], v[160:163], v[50:53]
	v_mfma_f32_16x16x32_bf16 v[42:45], v[204:207], v[160:163], v[42:45]
	v_mfma_f32_16x16x32_bf16 v[34:37], v[196:199], v[168:171], v[34:37]
	v_mfma_f32_16x16x32_bf16 v[26:29], v[204:207], v[168:171], v[26:29]
	v_mfma_f32_16x16x32_bf16 v[18:21], v[196:199], v[180:183], v[18:21]
	v_mfma_f32_16x16x32_bf16 v[10:13], v[204:207], v[180:183], v[10:13]
	v_mfma_f32_16x16x32_bf16 v[6:9], v[196:199], v[188:191], v[6:9]
	v_mfma_f32_16x16x32_bf16 v[2:5], v[204:207], v[188:191], v[2:5]
	v_mfma_f32_16x16x32_bf16 v[50:53], v[200:203], v[164:167], v[50:53]
	v_mfma_f32_16x16x32_bf16 v[42:45], v[226:229], v[164:167], v[42:45]
	v_mfma_f32_16x16x32_bf16 v[34:37], v[200:203], v[172:175], v[34:37]
	v_mfma_f32_16x16x32_bf16 v[26:29], v[226:229], v[172:175], v[26:29]
	v_mfma_f32_16x16x32_bf16 v[18:21], v[200:203], v[184:187], v[18:21]
	v_mfma_f32_16x16x32_bf16 v[10:13], v[226:229], v[184:187], v[10:13]
	v_mfma_f32_16x16x32_bf16 v[6:9], v[200:203], v[192:195], v[6:9]
	v_mfma_f32_16x16x32_bf16 v[2:5], v[226:229], v[192:195], v[2:5]
	s_add_i32 s67, s67, 2
	s_add_u32 s65, s65, 0x100
	s_addc_u32 s66, s66, 0
	s_cmp_gt_u32 s67, 41
	s_mov_b64 s[8:9], s[10:11]
	s_barrier
	s_cbranch_scc0 .LBB0_547
	v_readlane_b32 s8, v255, 27
	s_cmp_ge_i32 s64, s8
	s_cselect_b32 s8, s25, 0
	s_add_i32 s10, s64, s8
	s_sub_i32 s8, s10, 32
	s_lshl_b32 s9, s61, 8
	s_ashr_i32 s8, s8, 3
	s_or_b32 s9, s9, s50
	v_mov_b32_e32 v130, v1
	v_mov_b32_e32 v159, v156
	s_mul_i32 s8, s8, 6
	s_cmp_gt_i32 s10, 31
	s_cselect_b32 s8, s8, 0xc0
	v_lshl_add_u32 v130, v130, 2, s9
	s_ashr_i32 s9, s8, 31
	s_lshl_b64 s[8:9], s[8:9], 12
	v_readlane_b32 s12, v255, 14
	v_readlane_b32 s13, v255, 15
	s_add_u32 s8, s12, s8
	v_ashrrev_i32_e32 v131, 31, v130
	s_addc_u32 s9, s13, s9
	v_lshlrev_b64 v[154:155], 2, v[130:131]
	v_lshl_add_u64 v[130:131], s[8:9], 0, v[154:155]
	s_mov_b64 s[8:9], 0x5000
	v_lshl_add_u64 v[132:133], v[130:131], 0, s[8:9]
	s_movk_i32 s8, 0x5000
	v_add_co_u32_e32 v130, vcc, s8, v130
	s_lshl_b32 s8, s10, 8
	s_add_i32 s8, s8, s44
	v_add_u32_e32 v160, s8, v159
	v_ashrrev_i32_e32 v161, 31, v160
	v_readlane_b32 s8, v254, 0
	v_lshlrev_b64 v[160:161], 12, v[160:161]
	v_readlane_b32 s9, v254, 1
	v_addc_co_u32_e32 v131, vcc, 0, v131, vcc
	s_nop 0
	v_lshl_add_u64 v[160:161], s[8:9], 0, v[160:161]
	v_lshl_add_u64 v[154:155], v[160:161], 0, v[154:155]
	v_add_co_u32_e32 v176, vcc, s45, v154
	global_load_dwordx4 v[138:141], v[132:133], off offset:64
	global_load_dwordx4 v[134:137], v[132:133], off offset:512
	global_load_dwordx4 v[142:145], v[130:131], off
	s_nop 0
	global_load_dwordx4 v[130:133], v[132:133], off offset:576
	v_addc_co_u32_e32 v177, vcc, 0, v155, vcc
	v_add_co_u32_e32 v208, vcc, s19, v154
	global_load_dwordx4 v[160:163], v[154:155], off nt
	global_load_dwordx4 v[164:167], v[154:155], off offset:64 nt
	global_load_dwordx4 v[168:171], v[154:155], off offset:512 nt
	global_load_dwordx4 v[172:175], v[154:155], off offset:576 nt
	v_addc_co_u32_e32 v209, vcc, 0, v155, vcc
	v_add_co_u32_e32 v246, vcc, s88, v154
	global_load_dwordx4 v[180:183], v[176:177], off nt
	global_load_dwordx4 v[184:187], v[176:177], off offset:64 nt
	global_load_dwordx4 v[188:191], v[176:177], off offset:512 nt
	global_load_dwordx4 v[192:195], v[176:177], off offset:576 nt
	v_addc_co_u32_e32 v247, vcc, 0, v155, vcc
	global_load_dwordx4 v[196:199], v[208:209], off nt
	global_load_dwordx4 v[200:203], v[208:209], off offset:64 nt
	global_load_dwordx4 v[204:207], v[208:209], off offset:512 nt
	global_load_dwordx4 v[226:229], v[208:209], off offset:576 nt
	global_load_dwordx4 v[230:233], v[246:247], off nt
	global_load_dwordx4 v[234:237], v[246:247], off offset:64 nt
	global_load_dwordx4 v[238:241], v[246:247], off offset:512 nt
	global_load_dwordx4 v[242:245], v[246:247], off offset:576 nt
	s_mov_b64 s[8:9], 0x30000
	v_lshl_add_u64 v[248:249], v[154:155], 0, s[84:85]
	v_lshl_add_u64 v[250:251], v[154:155], 0, s[82:83]
	v_lshl_add_u64 v[252:253], v[154:155], 0, s[8:9]
	s_waitcnt vmcnt(0)
;     __device__ __forceinline__ void operator()(const AccT& acc, const Unit& u, int wr, int wc, int fr, int fq) const {
;     ...
;                     for (int n = 0; n < 2; ++n) xo[m][bj][n] = *(const f32x4*)(sbase + (size_t)(ai * 128 + m * 16) * 1024 + bj * 128 + n * 16);
;             __builtin_amdgcn_sched_barrier(0);
; #pragma unroll
;             for (int m = 0; m < 4; ++m) { float* rowp = X + (size_t)(row0 + ai * 128 + m * 16) * 1024 + col0;
; #pragma unroll
;                 for (int bj = 0; bj < 2; ++bj)
; #pragma unroll
;                     for (int n = 0; n < 2; ++n) *(f32x4*)(rowp + bj * 128 + n * 16) = xo[m][bj][n] + gv[bj][n] * acc[ai][bj][m][n]; }
	v_pk_fma_f32 v[108:109], v[108:109], v[132:133], v[174:175]
	v_pk_fma_f32 v[106:107], v[106:107], v[130:131], v[172:173]
	v_pk_fma_f32 v[92:93], v[92:93], v[132:133], v[194:195]
	v_pk_fma_f32 v[90:91], v[90:91], v[130:131], v[192:193]
	v_pk_fma_f32 v[76:77], v[76:77], v[132:133], v[228:229]
	v_pk_fma_f32 v[74:75], v[74:75], v[130:131], v[226:227]
	global_store_dwordx4 v[154:155], v[106:109], off offset:576
	global_store_dwordx4 v[248:249], v[90:93], off offset:576
	global_store_dwordx4 v[250:251], v[74:77], off offset:576
	v_pk_fma_f32 v[108:109], v[120:121], v[144:145], v[182:183]
	v_pk_fma_f32 v[106:107], v[118:119], v[142:143], v[180:181]
	v_pk_fma_f32 v[92:93], v[104:105], v[144:145], v[198:199]
	v_pk_fma_f32 v[90:91], v[102:103], v[142:143], v[196:197]
	v_pk_fma_f32 v[76:77], v[88:89], v[144:145], v[232:233]
	v_pk_fma_f32 v[74:75], v[86:87], v[142:143], v[230:231]
	v_pk_fma_f32 v[128:129], v[128:129], v[144:145], v[162:163]
	v_pk_fma_f32 v[126:127], v[126:127], v[142:143], v[160:161]
	v_pk_fma_f32 v[124:125], v[124:125], v[140:141], v[166:167]
	v_pk_fma_f32 v[122:123], v[122:123], v[138:139], v[164:165]
	v_pk_fma_f32 v[116:117], v[116:117], v[136:137], v[170:171]
	v_pk_fma_f32 v[114:115], v[114:115], v[134:135], v[168:169]
	global_store_dwordx4 v[176:177], v[106:109], off
	v_pk_fma_f32 v[100:101], v[100:101], v[136:137], v[190:191]
	v_pk_fma_f32 v[98:99], v[98:99], v[134:135], v[188:189]
	v_pk_fma_f32 v[108:109], v[112:113], v[140:141], v[186:187]
	v_pk_fma_f32 v[106:107], v[110:111], v[138:139], v[184:185]
	global_store_dwordx4 v[208:209], v[90:93], off
	v_pk_fma_f32 v[84:85], v[84:85], v[136:137], v[206:207]
	v_pk_fma_f32 v[82:83], v[82:83], v[134:135], v[204:205]
	v_pk_fma_f32 v[92:93], v[96:97], v[140:141], v[202:203]
	v_pk_fma_f32 v[90:91], v[94:95], v[138:139], v[200:201]
	global_store_dwordx4 v[246:247], v[74:77], off
	v_pk_fma_f32 v[72:73], v[72:73], v[136:137], v[240:241]
	v_pk_fma_f32 v[70:71], v[70:71], v[134:135], v[238:239]
	v_pk_fma_f32 v[76:77], v[80:81], v[140:141], v[236:237]
	v_pk_fma_f32 v[74:75], v[78:79], v[138:139], v[234:235]
	v_pk_fma_f32 v[68:69], v[68:69], v[132:133], v[244:245]
	v_pk_fma_f32 v[66:67], v[66:67], v[130:131], v[242:243]
	global_store_dwordx4 v[154:155], v[126:129], off
	global_store_dwordx4 v[154:155], v[122:125], off offset:64
	global_store_dwordx4 v[154:155], v[114:117], off offset:512
	global_store_dwordx4 v[248:249], v[106:109], off offset:64
	global_store_dwordx4 v[248:249], v[98:101], off offset:512
	global_store_dwordx4 v[250:251], v[90:93], off offset:64
	global_store_dwordx4 v[250:251], v[82:85], off offset:512
	global_store_dwordx4 v[252:253], v[74:77], off offset:64
	global_store_dwordx4 v[252:253], v[70:73], off offset:512
	global_store_dwordx4 v[252:253], v[66:69], off offset:576
	s_mov_b64 s[8:9], 0x80000
	v_lshl_add_u64 v[160:161], v[154:155], 0, s[8:9]
	s_mov_b32 s8, 0x80000
	v_add_co_u32_e32 v162, vcc, s8, v154
	s_mov_b64 s[8:9], 0x90000
	s_nop 0
	v_addc_co_u32_e32 v163, vcc, 0, v155, vcc
	v_lshl_add_u64 v[164:165], v[154:155], 0, s[8:9]
	s_mov_b32 s8, 0x90000
	v_add_co_u32_e32 v166, vcc, s8, v154
	s_mov_b64 s[8:9], 0xa0000
	s_nop 0
	v_addc_co_u32_e32 v167, vcc, 0, v155, vcc
	v_lshl_add_u64 v[168:169], v[154:155], 0, s[8:9]
	s_mov_b32 s8, 0xa0000
	v_add_co_u32_e32 v170, vcc, s8, v154
	s_mov_b64 s[8:9], 0xb0000
	s_nop 0
	v_addc_co_u32_e32 v171, vcc, 0, v155, vcc
	v_lshl_add_u64 v[172:173], v[154:155], 0, s[8:9]
	s_mov_b32 s8, 0xb0000
	v_add_co_u32_e32 v154, vcc, s8, v154
	global_load_dwordx4 v[66:69], v[162:163], off nt
	global_load_dwordx4 v[70:73], v[162:163], off offset:64 nt
	global_load_dwordx4 v[74:77], v[162:163], off offset:512 nt
	global_load_dwordx4 v[78:81], v[162:163], off offset:576 nt
	v_addc_co_u32_e32 v155, vcc, 0, v155, vcc
	global_load_dwordx4 v[82:85], v[166:167], off nt
	global_load_dwordx4 v[86:89], v[166:167], off offset:64 nt
	global_load_dwordx4 v[90:93], v[166:167], off offset:512 nt
	global_load_dwordx4 v[94:97], v[166:167], off offset:576 nt
	global_load_dwordx4 v[98:101], v[170:171], off nt
	global_load_dwordx4 v[102:105], v[170:171], off offset:64 nt
	global_load_dwordx4 v[106:109], v[170:171], off offset:512 nt
	global_load_dwordx4 v[110:113], v[170:171], off offset:576 nt
	global_load_dwordx4 v[114:117], v[154:155], off nt
	global_load_dwordx4 v[118:121], v[154:155], off offset:64 nt
	global_load_dwordx4 v[122:125], v[154:155], off offset:512 nt
	global_load_dwordx4 v[126:129], v[154:155], off offset:576 nt
	s_waitcnt vmcnt(0)
; #define PG8_WAIT_V(n) asm volatile("s_waitcnt vmcnt(" #n ")" ::: "memory")
; #define PG8_BAR __builtin_amdgcn_s_barrier()
; template <class Epi>
; __device__ __forceinline__ void gemm_phase(LAS unsigned char* lds, const Gemm g, const Epi& E) {
;     ...
;         cur = nxt; cA = nA; cB = nB; ++ui;
;     }
;     PG8_WAIT_V(0);
;     if (wr == 0) PG8_BAR;
;     PG8_BAR;
;     __device__ __forceinline__ void operator()(const AccT& acc, const Unit& u, int wr, int wc, int fr, int fq) const {
;     ...
;             for (int m = 0; m < 4; ++m) { float* rowp = X + (size_t)(row0 + ai * 128 + m * 16) * 1024 + col0;
; #pragma unroll
;                 for (int bj = 0; bj < 2; ++bj)
; #pragma unroll
;                     for (int n = 0; n < 2; ++n) *(f32x4*)(rowp + bj * 128 + n * 16) = xo[m][bj][n] + gv[bj][n] * acc[ai][bj][m][n]; }
	v_pk_fma_f32 v[44:45], v[44:45], v[132:133], v[80:81]
	v_pk_fma_f32 v[42:43], v[42:43], v[130:131], v[78:79]
	v_pk_fma_f32 v[28:29], v[28:29], v[132:133], v[96:97]
	v_pk_fma_f32 v[26:27], v[26:27], v[130:131], v[94:95]
	v_pk_fma_f32 v[12:13], v[12:13], v[132:133], v[112:113]
	v_pk_fma_f32 v[10:11], v[10:11], v[130:131], v[110:111]
	global_store_dwordx4 v[160:161], v[42:45], off offset:576
	global_store_dwordx4 v[164:165], v[26:29], off offset:576
	global_store_dwordx4 v[168:169], v[10:13], off offset:576
	v_pk_fma_f32 v[44:45], v[56:57], v[144:145], v[84:85]
	v_pk_fma_f32 v[42:43], v[54:55], v[142:143], v[82:83]
	v_pk_fma_f32 v[28:29], v[40:41], v[144:145], v[100:101]
	v_pk_fma_f32 v[26:27], v[38:39], v[142:143], v[98:99]
	v_pk_fma_f32 v[12:13], v[24:25], v[144:145], v[116:117]
	v_pk_fma_f32 v[10:11], v[22:23], v[142:143], v[114:115]
	v_pk_fma_f32 v[64:65], v[64:65], v[144:145], v[68:69]
	v_pk_fma_f32 v[62:63], v[62:63], v[142:143], v[66:67]
	v_pk_fma_f32 v[60:61], v[60:61], v[140:141], v[72:73]
	v_pk_fma_f32 v[58:59], v[58:59], v[138:139], v[70:71]
	v_pk_fma_f32 v[52:53], v[52:53], v[136:137], v[76:77]
	v_pk_fma_f32 v[50:51], v[50:51], v[134:135], v[74:75]
	global_store_dwordx4 v[166:167], v[42:45], off
	v_pk_fma_f32 v[36:37], v[36:37], v[136:137], v[92:93]
	v_pk_fma_f32 v[34:35], v[34:35], v[134:135], v[90:91]
	v_pk_fma_f32 v[44:45], v[48:49], v[140:141], v[88:89]
	v_pk_fma_f32 v[42:43], v[46:47], v[138:139], v[86:87]
	global_store_dwordx4 v[170:171], v[26:29], off
	v_pk_fma_f32 v[20:21], v[20:21], v[136:137], v[108:109]
	v_pk_fma_f32 v[18:19], v[18:19], v[134:135], v[106:107]
	v_pk_fma_f32 v[28:29], v[32:33], v[140:141], v[104:105]
	v_pk_fma_f32 v[26:27], v[30:31], v[138:139], v[102:103]
	global_store_dwordx4 v[154:155], v[10:13], off
	v_pk_fma_f32 v[8:9], v[8:9], v[136:137], v[124:125]
	v_pk_fma_f32 v[6:7], v[6:7], v[134:135], v[122:123]
	v_pk_fma_f32 v[12:13], v[16:17], v[140:141], v[120:121]
	v_pk_fma_f32 v[10:11], v[14:15], v[138:139], v[118:119]
	v_pk_fma_f32 v[4:5], v[4:5], v[132:133], v[128:129]
	v_pk_fma_f32 v[2:3], v[2:3], v[130:131], v[126:127]
	global_store_dwordx4 v[162:163], v[62:65], off
	global_store_dwordx4 v[160:161], v[58:61], off offset:64
	global_store_dwordx4 v[160:161], v[50:53], off offset:512
	global_store_dwordx4 v[164:165], v[42:45], off offset:64
	global_store_dwordx4 v[164:165], v[34:37], off offset:512
	global_store_dwordx4 v[168:169], v[26:29], off offset:64
	global_store_dwordx4 v[168:169], v[18:21], off offset:512
	global_store_dwordx4 v[172:173], v[10:13], off offset:64
	global_store_dwordx4 v[172:173], v[6:9], off offset:512
	global_store_dwordx4 v[172:173], v[2:5], off offset:576
	s_and_b64 vcc, exec, s[2:3]
	s_mov_b32 s61, s59
	s_mov_b32 s64, s60
	s_mov_b64 s[10:11], s[6:7]
	s_mov_b64 s[8:9], s[4:5]
	s_cbranch_vccz .LBB0_540
	s_waitcnt vmcnt(0)
	s_cmpk_gt_u32 s1, 0xff
	s_movk_i32 s36, 0xf000
	s_cbranch_scc1 .LBB0_551
	s_barrier
